# v7 + s_setprio 1/0 around the QK and P.V MFMA clusters of the MLA loop (wave-priority ping-pong between the two waves per SIMD)
# baseline (speedup 1.0000x reference)
; #define LAS __attribute__((address_space(3)))
; template <int DK16>
; __device__ __forceinline__ f32x16 qk_sub(const LAS unsigned char* Kt, int ks, int sub, const bf16x8 (&qf)[DK16], int r32, int hi) {
;     f32x16 s;
; #pragma unroll
;     for (int v = 0; v < 16; ++v) s[v] = 0.f;
;     const LAS unsigned char* p = Kt + (sub * 32 + r32) * ks + hi * 16;
; #pragma unroll
;     for (int dk = 0; dk < DK16; ++dk) { const bf16x8 kf = *(const LAS bf16x8*)(p + dk * 32); s = __builtin_amdgcn_mfma_f32_32x32x16_bf16(kf, qf[dk], s, 0, 0, 0); }
;     return s;
; }
; template <int D, int DV, int MODE, bool HASBIAS, bool JOINT, bool DEFER, class KA, class VA, class PF, class BF, class VF, class NM, class WS, class CB> ...
;     ...
;         const bool sk0 = wskip(t, 0), sk1 = wskip(t, 1);
;         if (JOINT && MODE != 2 && !sk0 && !sk1) {
;             f32x16 s0 = qk_sub<D / 16>(cur, KS, 0, qf, r32, hi); if (DEFER) __builtin_amdgcn_sched_barrier(0); f32x16 s1 = qk_sub<D / 16>(cur, KS, 1, qf, r32, hi);
.LBB0_1016:
	s_add_i32 s10, s49, 0xffffff81
	s_cmp_le_i32 s10, s39
	s_cselect_b64 s[8:9], -1, 0
	s_add_i32 s11, s49, 0xffffffa1
	s_cmp_le_i32 s11, s39
	s_cselect_b64 s[18:19], -1, 0
	s_max_i32 s10, s10, s11
	s_cmp_gt_i32 s10, s39
	s_cselect_b64 s[10:11], -1, 0
	s_andn2_b64 vcc, exec, s[10:11]
	s_cbranch_vccz .LBB0_1027
	v_add_u32_e32 v1, v173, v2
	ds_read_b128 v[36:39], v1
	ds_read_b128 v[52:55], v1 offset:32
	s_cmp_ge_u32 s53, s38
	s_cbranch_scc1 .Lmla_qkp1
	s_lshl_b32 s74, s52, 6
	s_mov_b64 s[12:13], 0x340fff80
	s_mov_b64 s[100:101], 0x24120000
	s_add_i32 s10, s49, 0xffffffa0
	s_sub_i32 s11, s49, 64
	s_max_i32 s10, s10, s11
	s_cmp_le_i32 s10, s30
	s_cselect_b64 s[16:17], -1, 0
	s_and_b64 vcc, exec, s[16:17]
	s_setprio 1
	s_waitcnt lgkmcnt(0)
	v_mfma_f32_32x32x16_bf16 v[36:51], v[36:39], v[84:87], 0
	ds_read_b128 v[68:71], v1 offset:6688
	v_lshl_add_u64 v[72:73], v[136:137], 0, s[74:75]
	v_lshlrev_b64 v[72:73], 6, v[72:73]
	v_lshl_add_u64 v[72:73], v[140:141], 0, v[72:73]
	v_lshl_add_u64 v[72:73], v[72:73], 0, s[12:13]
	v_mfma_f32_32x32x16_bf16 v[36:51], v[52:55], v[88:91], v[36:51]
	ds_read_b128 v[52:55], v1 offset:64
	v_lshl_add_u64 v[74:75], s[20:21], 0, v[146:147]
	v_lshl_add_u64 v[74:75], v[74:75], 0, s[100:101]
	v_cndmask_b32_e64 v72, v74, v72, s[44:45]
	v_cndmask_b32_e64 v73, v75, v73, s[44:45]
	s_waitcnt lgkmcnt(0)
	v_mfma_f32_32x32x16_bf16 v[36:51], v[52:55], v[92:95], v[36:51]
	global_load_dwordx4 v[108:111], v[72:73], off
	ds_read_b128 v[52:55], v1 offset:96
	v_lshl_add_u64 v[72:73], v[138:139], 0, s[74:75]
	v_lshlrev_b64 v[72:73], 6, v[72:73]
	v_lshl_add_u64 v[72:73], v[142:143], 0, v[72:73]
	v_lshl_add_u64 v[72:73], v[72:73], 0, s[12:13]
	s_waitcnt lgkmcnt(0)
	v_mfma_f32_32x32x16_bf16 v[36:51], v[52:55], v[96:99], v[36:51]
	ds_read_b128 v[52:55], v1 offset:128
	v_lshl_add_u64 v[74:75], s[20:21], 0, v[148:149]
	v_lshl_add_u64 v[74:75], v[74:75], 0, s[100:101]
	v_cndmask_b32_e64 v72, v74, v72, s[46:47]
	v_cndmask_b32_e64 v73, v75, v73, s[46:47]
	s_waitcnt lgkmcnt(0)
	v_mfma_f32_32x32x16_bf16 v[36:51], v[52:55], v[100:103], v[36:51]
	ds_read_b128 v[52:55], v1 offset:160
	s_cmp_eq_u64 s[42:43], 0
	s_cbranch_scc1 .Lmla_c2s1
	global_load_dwordx4 v[112:115], v[72:73], off
.Lmla_c2s1:
	v_lshl_add_u64 v[74:75], s[20:21], 0, v[144:145]
	s_mov_b64 s[12:13], 0x28100000
	v_lshl_add_u64 v[74:75], v[74:75], 0, s[12:13]
	s_waitcnt lgkmcnt(0)
	v_mfma_f32_32x32x16_bf16 v[36:51], v[52:55], v[104:107], v[36:51]
	global_load_dwordx4 v[116:119], v[74:75], off offset:256
	ds_read_b128 v[52:55], v1 offset:6656
	s_waitcnt lgkmcnt(0)
	v_mfma_f32_32x32x16_bf16 v[52:67], v[52:55], v[84:87], 0
	v_mfma_f32_32x32x16_bf16 v[52:67], v[68:71], v[88:91], v[52:67]
	ds_read_b128 v[68:71], v1 offset:6720
	s_waitcnt lgkmcnt(0)
	v_mfma_f32_32x32x16_bf16 v[52:67], v[68:71], v[92:95], v[52:67]
	ds_read_b128 v[68:71], v1 offset:6752
	s_waitcnt lgkmcnt(0)
	v_mfma_f32_32x32x16_bf16 v[52:67], v[68:71], v[96:99], v[52:67]
	ds_read_b128 v[68:71], v1 offset:6784
	s_waitcnt lgkmcnt(0)
	v_mfma_f32_32x32x16_bf16 v[52:67], v[68:71], v[100:103], v[52:67]
	ds_read_b128 v[68:71], v1 offset:6816
	s_waitcnt lgkmcnt(0)
	v_mfma_f32_32x32x16_bf16 v[52:67], v[68:71], v[104:107], v[52:67]
	s_setprio 0
	s_cbranch_vccnz .LBB0_1019
	s_branch .Lmla_m1
.Lmla_qkp1:
	s_add_i32 s10, s49, 0xffffffa0
	s_sub_i32 s11, s49, 64
	s_max_i32 s10, s10, s11
	s_setprio 1
	s_waitcnt lgkmcnt(0)
	v_mfma_f32_32x32x16_bf16 v[36:51], v[36:39], v[84:87], 0
	s_cmp_le_i32 s10, s30
	s_cselect_b64 s[16:17], -1, 0
	s_and_b64 vcc, exec, s[16:17]
	ds_read_b128 v[68:71], v1 offset:6688
	v_mfma_f32_32x32x16_bf16 v[36:51], v[52:55], v[88:91], v[36:51]
	ds_read_b128 v[52:55], v1 offset:64
	s_waitcnt lgkmcnt(0)
	v_mfma_f32_32x32x16_bf16 v[36:51], v[52:55], v[92:95], v[36:51]
	ds_read_b128 v[52:55], v1 offset:96
	s_waitcnt lgkmcnt(0)
	v_mfma_f32_32x32x16_bf16 v[36:51], v[52:55], v[96:99], v[36:51]
	ds_read_b128 v[52:55], v1 offset:128
	s_waitcnt lgkmcnt(0)
	v_mfma_f32_32x32x16_bf16 v[36:51], v[52:55], v[100:103], v[36:51]
	ds_read_b128 v[52:55], v1 offset:160
	s_waitcnt lgkmcnt(0)
	v_mfma_f32_32x32x16_bf16 v[36:51], v[52:55], v[104:107], v[36:51]
	ds_read_b128 v[52:55], v1 offset:6656
	s_waitcnt lgkmcnt(0)
	v_mfma_f32_32x32x16_bf16 v[52:67], v[52:55], v[84:87], 0
	v_mfma_f32_32x32x16_bf16 v[52:67], v[68:71], v[88:91], v[52:67]
	ds_read_b128 v[68:71], v1 offset:6720
	s_waitcnt lgkmcnt(0)
	v_mfma_f32_32x32x16_bf16 v[52:67], v[68:71], v[92:95], v[52:67]
	ds_read_b128 v[68:71], v1 offset:6752
	s_waitcnt lgkmcnt(0)
	v_mfma_f32_32x32x16_bf16 v[52:67], v[68:71], v[96:99], v[52:67]
	ds_read_b128 v[68:71], v1 offset:6784
	s_waitcnt lgkmcnt(0)
	v_mfma_f32_32x32x16_bf16 v[52:67], v[68:71], v[100:103], v[52:67]
	ds_read_b128 v[68:71], v1 offset:6816
	s_waitcnt lgkmcnt(0)
	v_mfma_f32_32x32x16_bf16 v[52:67], v[68:71], v[104:107], v[52:67]
	s_setprio 0
	s_cbranch_vccnz .LBB0_1019

; __device__ __forceinline__ unsigned cvt_pk_bf16(float lo, float hi) { unsigned r; asm volatile("v_cvt_pk_bf16_f32 %0, %1, %2" : "=v"(r) : "v"(lo), "v"(hi)); return r; }
; #define LAS __attribute__((address_space(3)))
; __device__ __forceinline__ float fast_exp2(float x) { return __builtin_amdgcn_exp2f(x); }
; template <int DV32>
; __device__ __forceinline__ void pv_sub(f32x16 (&o)[DV32], const LAS unsigned char* Vt, int vs, int sub, const f32x16& p, int r32, int hi) {
; #pragma unroll
;     for (int kb = 0; kb < 2; ++kb) {
;         u32x4 pw; pw.x = cvt_pk_bf16(p[8 * kb + 0], p[8 * kb + 1]); pw.y = cvt_pk_bf16(p[8 * kb + 2], p[8 * kb + 3]); pw.z = cvt_pk_bf16(p[8 * kb + 4], p[8 * kb + 5]); pw.w = cvt_pk_bf16(p[8 * kb + 6], p[8 * kb + 7]);
;         const bf16x8 pf = __builtin_bit_cast(bf16x8, pw);
; #pragma unroll
;         for (int i = 0; i < DV32; ++i) {
;             const bf16x8 vf = *(const LAS bf16x8*)(Vt + (32 * i + r32) * vs + sub * 64 + kb * 32 + hi * 16);
;             o[i] = __builtin_amdgcn_mfma_f32_32x32x16_bf16(vf, pf, o[i], 0, 0, 0);
;         }
;     }
; }
; template <int D, int DV, int MODE, bool HASBIAS, bool JOINT, bool DEFER, class KA, class VA, class PF, class BF, class VF, class NM, class WS, class CB> ...
;     ...
;                 for (int v = 0; v < 16; ++v) { const float p0 = fast_exp2(s0[v] - mn), p1 = fast_exp2(s1[v] - mn); s0[v] = p0; s1[v] = p1; sum0 += p0; sum1 += p1; }
;             }
;             if (grow) {
;                 const float alpha = fast_exp2(m - mn); l *= alpha;
;                 if (MODE == 0) {
; #pragma unroll
;                     for (int i = 0; i < DV / 32; ++i)
; #pragma unroll
;                         for (int v = 0; v < 16; ++v) o[i][v] *= alpha;
;                 }
;             }
;             l += sum0 + sum1; m = mn;
;             if (MODE == 0) {
;                 if (defer_wave) { pp0 = pack8(s0, 0); pp1 = pack8(s0, 1); pp2 = pack8(s1, 0); pp3 = pack8(s1, 1); pend = vslot; }
;                 else { pv_sub<DV / 32>(o, curv, VS, 0, s0, r32, hi); pv_sub<DV / 32>(o, curv, VS, 1, s1, r32, hi); }
.Lmla_es1_done:
	v_add_u32_e32 v1, v175, v184
	v_cvt_pk_bf16_f32 v194, v151, v157
	v_cvt_pk_bf16_f32 v195, v153, v161
	ds_read_b128 v[198:201], v1 offset:26624
	ds_read_b128 v[48:51], v1 offset:31232
	v_cvt_pk_bf16_f32 v196, v155, v165
	v_cvt_pk_bf16_f32 v197, v159, v167
	s_mov_b64 s[10:11], 0
	v_add_f32_e32 v168, 0, v150
	v_add_f32_e32 v169, 0, v151
	v_cvt_pk_bf16_f32 v36, v69, v75
	v_add_f32_e32 v168, v156, v168
	v_add_f32_e32 v169, v157, v169
	s_setprio 1
	s_waitcnt lgkmcnt(1)
	v_mfma_f32_32x32x16_bf16 v[4:19], v[198:201], v[194:197], v[4:19]
	ds_read_b128 v[52:55], v1 offset:26656
	ds_read_b128 v[56:59], v1 offset:31264
	v_cvt_pk_bf16_f32 v37, v71, v79
	v_add_f32_e32 v168, v152, v168
	v_add_f32_e32 v169, v153, v169
	v_cvt_pk_bf16_f32 v38, v73, v81
	v_add_f32_e32 v168, v160, v168
	v_add_f32_e32 v169, v161, v169
	s_waitcnt lgkmcnt(2)
	v_mfma_f32_32x32x16_bf16 v[20:35], v[48:51], v[194:197], v[20:35]
	v_cvt_pk_bf16_f32 v39, v77, v83
	v_add_f32_e32 v168, v154, v168
	v_add_f32_e32 v169, v155, v169
	v_cvt_pk_bf16_f32 v40, v150, v156
	v_add_f32_e32 v168, v164, v168
	v_add_f32_e32 v169, v165, v169
	s_waitcnt lgkmcnt(1)
	v_mfma_f32_32x32x16_bf16 v[4:19], v[52:55], v[36:39], v[4:19]
	ds_read_b128 v[60:63], v1 offset:26688
	ds_read_b128 v[64:67], v1 offset:31296
	v_cvt_pk_bf16_f32 v41, v152, v160
	v_add_f32_e32 v168, v158, v168
	v_add_f32_e32 v169, v159, v169
	v_cvt_pk_bf16_f32 v42, v154, v164
	v_add_f32_e32 v168, v166, v168
	v_add_f32_e32 v169, v167, v169
	s_waitcnt lgkmcnt(2)
	v_mfma_f32_32x32x16_bf16 v[20:35], v[56:59], v[36:39], v[20:35]
	v_cvt_pk_bf16_f32 v43, v158, v166
	v_add_f32_e32 v168, v68, v168
	v_add_f32_e32 v169, v69, v169
	v_cvt_pk_bf16_f32 v44, v68, v74
	v_add_f32_e32 v168, v74, v168
	v_add_f32_e32 v169, v75, v169
	s_waitcnt lgkmcnt(1)
	v_mfma_f32_32x32x16_bf16 v[4:19], v[60:63], v[40:43], v[4:19]
	ds_read_b128 v[198:201], v1 offset:26720
	ds_read_b128 v[48:51], v1 offset:31328
	v_cvt_pk_bf16_f32 v45, v70, v78
	v_add_f32_e32 v168, v70, v168
	v_add_f32_e32 v169, v71, v169
	v_cvt_pk_bf16_f32 v46, v72, v80
	v_add_f32_e32 v168, v78, v168
	v_add_f32_e32 v169, v79, v169
	s_waitcnt lgkmcnt(2)
	v_mfma_f32_32x32x16_bf16 v[20:35], v[64:67], v[40:43], v[20:35]
	v_cvt_pk_bf16_f32 v47, v76, v82
	v_add_f32_e32 v168, v72, v168
	v_add_f32_e32 v169, v73, v169
	v_add_f32_e32 v168, v80, v168
	v_add_f32_e32 v169, v81, v169
	s_waitcnt lgkmcnt(1)
	v_mfma_f32_32x32x16_bf16 v[4:19], v[198:201], v[44:47], v[4:19]
	v_add_f32_e32 v168, v76, v168
	v_add_f32_e32 v169, v77, v169
	v_add_f32_e32 v168, v82, v168
	v_add_f32_e32 v169, v83, v169
	s_waitcnt lgkmcnt(0)
	v_mfma_f32_32x32x16_bf16 v[20:35], v[48:51], v[44:47], v[20:35]
	s_setprio 0
	v_add_f32_e32 v168, v168, v169
	v_add_f32_e32 v192, v168, v192
	s_add_i32 s10, s48, -2
	s_cmp_lt_u32 s10, s38
	s_cselect_b64 s[8:9], -1, 0
	s_branch .LBB0_1057

; #define LAS __attribute__((address_space(3)))
; template <int DK16>
; __device__ __forceinline__ f32x16 qk_sub(const LAS unsigned char* Kt, int ks, int sub, const bf16x8 (&qf)[DK16], int r32, int hi) {
;     f32x16 s;
; #pragma unroll
;     for (int v = 0; v < 16; ++v) s[v] = 0.f;
;     const LAS unsigned char* p = Kt + (sub * 32 + r32) * ks + hi * 16;
; #pragma unroll
;     for (int dk = 0; dk < DK16; ++dk) { const bf16x8 kf = *(const LAS bf16x8*)(p + dk * 32); s = __builtin_amdgcn_mfma_f32_32x32x16_bf16(kf, qf[dk], s, 0, 0, 0); }
;     return s;
; }
; template <int D, int DV, int MODE, bool HASBIAS, bool JOINT, bool DEFER, class KA, class VA, class PF, class BF, class VF, class NM, class WS, class CB> ...
;     ...
;         const bool sk0 = wskip(t, 0), sk1 = wskip(t, 1);
;         if (JOINT && MODE != 2 && !sk0 && !sk1) {
;             f32x16 s0 = qk_sub<D / 16>(cur, KS, 0, qf, r32, hi); if (DEFER) __builtin_amdgcn_sched_barrier(0); f32x16 s1 = qk_sub<D / 16>(cur, KS, 1, qf, r32, hi);
.LBB0_1072:
	s_sub_i32 s10, s49, 63
	s_cmp_le_i32 s10, s39
	s_cselect_b64 s[8:9], -1, 0
	s_sub_i32 s11, s49, 31
	s_cmp_le_i32 s11, s39
	s_cselect_b64 s[18:19], -1, 0
	s_max_i32 s10, s10, s11
	s_cmp_gt_i32 s10, s39
	s_cselect_b64 s[10:11], -1, 0
	s_andn2_b64 vcc, exec, s[10:11]
	s_cbranch_vccz .LBB0_1084
	v_add_u32_e32 v1, v173, v2
	ds_read_b128 v[36:39], v1 offset:13312
	ds_read_b128 v[52:55], v1 offset:13344
	s_cmp_ge_u32 s48, s38
	s_cbranch_scc1 .Lmla_qkp2
	s_lshl_b32 s74, s54, 6
	s_add_i32 s74, s74, 0xc0
	s_mov_b64 s[12:13], 0x340fff80
	s_mov_b64 s[100:101], 0x24130000
	s_sub_i32 s10, s49, 32
	s_max_i32 s10, s10, s49
	s_cmp_le_i32 s10, s30
	s_cselect_b64 s[16:17], -1, 0
	s_and_b64 vcc, exec, s[16:17]
	s_setprio 1
	s_waitcnt lgkmcnt(0)
	v_mfma_f32_32x32x16_bf16 v[36:51], v[36:39], v[84:87], 0
	ds_read_b128 v[68:71], v1 offset:20000
	v_lshl_add_u64 v[72:73], v[136:137], 0, s[74:75]
	v_lshlrev_b64 v[72:73], 6, v[72:73]
	v_lshl_add_u64 v[72:73], v[140:141], 0, v[72:73]
	v_lshl_add_u64 v[72:73], v[72:73], 0, s[12:13]
	v_mfma_f32_32x32x16_bf16 v[36:51], v[52:55], v[88:91], v[36:51]
	ds_read_b128 v[52:55], v1 offset:13376
	v_lshl_add_u64 v[74:75], s[20:21], 0, v[146:147]
	v_lshl_add_u64 v[74:75], v[74:75], 0, s[100:101]
	v_cndmask_b32_e64 v72, v74, v72, s[44:45]
	v_cndmask_b32_e64 v73, v75, v73, s[44:45]
	s_waitcnt lgkmcnt(0)
	v_mfma_f32_32x32x16_bf16 v[36:51], v[52:55], v[92:95], v[36:51]
	global_load_dwordx4 v[120:123], v[72:73], off
	ds_read_b128 v[52:55], v1 offset:13408
	v_lshl_add_u64 v[72:73], v[138:139], 0, s[74:75]
	v_lshlrev_b64 v[72:73], 6, v[72:73]
	v_lshl_add_u64 v[72:73], v[142:143], 0, v[72:73]
	v_lshl_add_u64 v[72:73], v[72:73], 0, s[12:13]
	s_waitcnt lgkmcnt(0)
	v_mfma_f32_32x32x16_bf16 v[36:51], v[52:55], v[96:99], v[36:51]
	ds_read_b128 v[52:55], v1 offset:13440
	v_lshl_add_u64 v[74:75], s[20:21], 0, v[148:149]
	v_lshl_add_u64 v[74:75], v[74:75], 0, s[100:101]
	v_cndmask_b32_e64 v72, v74, v72, s[46:47]
	v_cndmask_b32_e64 v73, v75, v73, s[46:47]
	s_waitcnt lgkmcnt(0)
	v_mfma_f32_32x32x16_bf16 v[36:51], v[52:55], v[100:103], v[36:51]
	ds_read_b128 v[52:55], v1 offset:13472
	s_cmp_eq_u64 s[42:43], 0
	s_cbranch_scc1 .Lmla_c2s2
	global_load_dwordx4 v[124:127], v[72:73], off
.Lmla_c2s2:
	v_lshl_add_u64 v[74:75], s[20:21], 0, v[144:145]
	s_mov_b64 s[12:13], 0x28100000
	v_lshl_add_u64 v[74:75], v[74:75], 0, s[12:13]
	s_waitcnt lgkmcnt(0)
	v_mfma_f32_32x32x16_bf16 v[36:51], v[52:55], v[104:107], v[36:51]
	global_load_dwordx4 v[128:131], v[74:75], off offset:384
	ds_read_b128 v[52:55], v1 offset:19968
	s_waitcnt lgkmcnt(0)
	v_mfma_f32_32x32x16_bf16 v[52:67], v[52:55], v[84:87], 0
	v_mfma_f32_32x32x16_bf16 v[52:67], v[68:71], v[88:91], v[52:67]
	ds_read_b128 v[68:71], v1 offset:20032
	s_waitcnt lgkmcnt(0)
	v_mfma_f32_32x32x16_bf16 v[52:67], v[68:71], v[92:95], v[52:67]
	ds_read_b128 v[68:71], v1 offset:20064
	s_waitcnt lgkmcnt(0)
	v_mfma_f32_32x32x16_bf16 v[52:67], v[68:71], v[96:99], v[52:67]
	ds_read_b128 v[68:71], v1 offset:20096
	s_waitcnt lgkmcnt(0)
	v_mfma_f32_32x32x16_bf16 v[52:67], v[68:71], v[100:103], v[52:67]
	ds_read_b128 v[68:71], v1 offset:20128
	s_waitcnt lgkmcnt(0)
	v_mfma_f32_32x32x16_bf16 v[52:67], v[68:71], v[104:107], v[52:67]
	s_setprio 0
	s_cbranch_vccnz .LBB0_1075
	s_branch .Lmla_m2
.Lmla_qkp2:
	s_sub_i32 s10, s49, 32
	s_max_i32 s10, s10, s49
	s_cmp_le_i32 s10, s30
	s_setprio 1
	s_waitcnt lgkmcnt(0)
	v_mfma_f32_32x32x16_bf16 v[36:51], v[36:39], v[84:87], 0
	s_cselect_b64 s[16:17], -1, 0
	s_and_b64 vcc, exec, s[16:17]
	ds_read_b128 v[68:71], v1 offset:20000
	v_mfma_f32_32x32x16_bf16 v[36:51], v[52:55], v[88:91], v[36:51]
	ds_read_b128 v[52:55], v1 offset:13376
	s_waitcnt lgkmcnt(0)
	v_mfma_f32_32x32x16_bf16 v[36:51], v[52:55], v[92:95], v[36:51]
	ds_read_b128 v[52:55], v1 offset:13408
	s_waitcnt lgkmcnt(0)
	v_mfma_f32_32x32x16_bf16 v[36:51], v[52:55], v[96:99], v[36:51]
	ds_read_b128 v[52:55], v1 offset:13440
	s_waitcnt lgkmcnt(0)
	v_mfma_f32_32x32x16_bf16 v[36:51], v[52:55], v[100:103], v[36:51]
	ds_read_b128 v[52:55], v1 offset:13472
	s_waitcnt lgkmcnt(0)
	v_mfma_f32_32x32x16_bf16 v[36:51], v[52:55], v[104:107], v[36:51]
	ds_read_b128 v[52:55], v1 offset:19968
	s_waitcnt lgkmcnt(0)
	v_mfma_f32_32x32x16_bf16 v[52:67], v[52:55], v[84:87], 0
	v_mfma_f32_32x32x16_bf16 v[52:67], v[68:71], v[88:91], v[52:67]
	ds_read_b128 v[68:71], v1 offset:20032
	s_waitcnt lgkmcnt(0)
	v_mfma_f32_32x32x16_bf16 v[52:67], v[68:71], v[92:95], v[52:67]
	ds_read_b128 v[68:71], v1 offset:20064
	s_waitcnt lgkmcnt(0)
	v_mfma_f32_32x32x16_bf16 v[52:67], v[68:71], v[96:99], v[52:67]
	ds_read_b128 v[68:71], v1 offset:20096
	s_waitcnt lgkmcnt(0)
	v_mfma_f32_32x32x16_bf16 v[52:67], v[68:71], v[100:103], v[52:67]
	ds_read_b128 v[68:71], v1 offset:20128
	s_waitcnt lgkmcnt(0)
	v_mfma_f32_32x32x16_bf16 v[52:67], v[68:71], v[104:107], v[52:67]
	s_setprio 0
	s_cbranch_vccnz .LBB0_1075

; __device__ __forceinline__ unsigned cvt_pk_bf16(float lo, float hi) { unsigned r; asm volatile("v_cvt_pk_bf16_f32 %0, %1, %2" : "=v"(r) : "v"(lo), "v"(hi)); return r; }
; #define LAS __attribute__((address_space(3)))
; __device__ __forceinline__ float fast_exp2(float x) { return __builtin_amdgcn_exp2f(x); }
; template <int DV32>
; __device__ __forceinline__ void pv_sub(f32x16 (&o)[DV32], const LAS unsigned char* Vt, int vs, int sub, const f32x16& p, int r32, int hi) {
; #pragma unroll
;     for (int kb = 0; kb < 2; ++kb) {
;         u32x4 pw; pw.x = cvt_pk_bf16(p[8 * kb + 0], p[8 * kb + 1]); pw.y = cvt_pk_bf16(p[8 * kb + 2], p[8 * kb + 3]); pw.z = cvt_pk_bf16(p[8 * kb + 4], p[8 * kb + 5]); pw.w = cvt_pk_bf16(p[8 * kb + 6], p[8 * kb + 7]);
;         const bf16x8 pf = __builtin_bit_cast(bf16x8, pw);
; #pragma unroll
;         for (int i = 0; i < DV32; ++i) {
;             const bf16x8 vf = *(const LAS bf16x8*)(Vt + (32 * i + r32) * vs + sub * 64 + kb * 32 + hi * 16);
;             o[i] = __builtin_amdgcn_mfma_f32_32x32x16_bf16(vf, pf, o[i], 0, 0, 0);
;         }
;     }
; }
; template <int D, int DV, int MODE, bool HASBIAS, bool JOINT, bool DEFER, class KA, class VA, class PF, class BF, class VF, class NM, class WS, class CB> ...
;     ...
;                 for (int v = 0; v < 16; ++v) { const float p0 = fast_exp2(s0[v] - mn), p1 = fast_exp2(s1[v] - mn); s0[v] = p0; s1[v] = p1; sum0 += p0; sum1 += p1; }
;             }
;             if (grow) {
;                 const float alpha = fast_exp2(m - mn); l *= alpha;
;                 if (MODE == 0) {
; #pragma unroll
;                     for (int i = 0; i < DV / 32; ++i)
; #pragma unroll
;                         for (int v = 0; v < 16; ++v) o[i][v] *= alpha;
;                 }
;             }
;             l += sum0 + sum1; m = mn;
;             if (MODE == 0) {
;                 if (defer_wave) { pp0 = pack8(s0, 0); pp1 = pack8(s0, 1); pp2 = pack8(s1, 0); pp3 = pack8(s1, 1); pend = vslot; }
;                 else { pv_sub<DV / 32>(o, curv, VS, 0, s0, r32, hi); pv_sub<DV / 32>(o, curv, VS, 1, s1, r32, hi); }
.Lmla_es2_done:
	v_add_u32_e32 v1, v175, v184
	v_cvt_pk_bf16_f32 v194, v151, v157
	v_cvt_pk_bf16_f32 v195, v153, v161
	ds_read_b128 v[198:201], v1 offset:35840
	ds_read_b128 v[48:51], v1 offset:40448
	v_cvt_pk_bf16_f32 v196, v155, v165
	v_cvt_pk_bf16_f32 v197, v159, v167
	s_mov_b64 s[10:11], 0
	v_add_f32_e32 v168, 0, v150
	v_add_f32_e32 v169, 0, v151
	v_cvt_pk_bf16_f32 v36, v69, v75
	v_add_f32_e32 v168, v156, v168
	v_add_f32_e32 v169, v157, v169
	s_setprio 1
	s_waitcnt lgkmcnt(1)
	v_mfma_f32_32x32x16_bf16 v[4:19], v[198:201], v[194:197], v[4:19]
	ds_read_b128 v[52:55], v1 offset:35872
	ds_read_b128 v[56:59], v1 offset:40480
	v_cvt_pk_bf16_f32 v37, v71, v79
	v_add_f32_e32 v168, v152, v168
	v_add_f32_e32 v169, v153, v169
	v_cvt_pk_bf16_f32 v38, v73, v81
	v_add_f32_e32 v168, v160, v168
	v_add_f32_e32 v169, v161, v169
	s_waitcnt lgkmcnt(2)
	v_mfma_f32_32x32x16_bf16 v[20:35], v[48:51], v[194:197], v[20:35]
	v_cvt_pk_bf16_f32 v39, v77, v83
	v_add_f32_e32 v168, v154, v168
	v_add_f32_e32 v169, v155, v169
	v_cvt_pk_bf16_f32 v40, v150, v156
	v_add_f32_e32 v168, v164, v168
	v_add_f32_e32 v169, v165, v169
	s_waitcnt lgkmcnt(1)
	v_mfma_f32_32x32x16_bf16 v[4:19], v[52:55], v[36:39], v[4:19]
	ds_read_b128 v[60:63], v1 offset:35904
	ds_read_b128 v[64:67], v1 offset:40512
	v_cvt_pk_bf16_f32 v41, v152, v160
	v_add_f32_e32 v168, v158, v168
	v_add_f32_e32 v169, v159, v169
	v_cvt_pk_bf16_f32 v42, v154, v164
	v_add_f32_e32 v168, v166, v168
	v_add_f32_e32 v169, v167, v169
	s_waitcnt lgkmcnt(2)
	v_mfma_f32_32x32x16_bf16 v[20:35], v[56:59], v[36:39], v[20:35]
	v_cvt_pk_bf16_f32 v43, v158, v166
	v_add_f32_e32 v168, v68, v168
	v_add_f32_e32 v169, v69, v169
	v_cvt_pk_bf16_f32 v44, v68, v74
	v_add_f32_e32 v168, v74, v168
	v_add_f32_e32 v169, v75, v169
	s_waitcnt lgkmcnt(1)
	v_mfma_f32_32x32x16_bf16 v[4:19], v[60:63], v[40:43], v[4:19]
	ds_read_b128 v[198:201], v1 offset:35936
	ds_read_b128 v[48:51], v1 offset:40544
	v_cvt_pk_bf16_f32 v45, v70, v78
	v_add_f32_e32 v168, v70, v168
	v_add_f32_e32 v169, v71, v169
	v_cvt_pk_bf16_f32 v46, v72, v80
	v_add_f32_e32 v168, v78, v168
	v_add_f32_e32 v169, v79, v169
	s_waitcnt lgkmcnt(2)
	v_mfma_f32_32x32x16_bf16 v[20:35], v[64:67], v[40:43], v[20:35]
	v_cvt_pk_bf16_f32 v47, v76, v82
	v_add_f32_e32 v168, v72, v168
	v_add_f32_e32 v169, v73, v169
	v_add_f32_e32 v168, v80, v168
	v_add_f32_e32 v169, v81, v169
	s_waitcnt lgkmcnt(1)
	v_mfma_f32_32x32x16_bf16 v[4:19], v[198:201], v[44:47], v[4:19]
	v_add_f32_e32 v168, v76, v168
	v_add_f32_e32 v169, v77, v169
	v_add_f32_e32 v168, v82, v168
	v_add_f32_e32 v169, v83, v169
	s_waitcnt lgkmcnt(0)
	v_mfma_f32_32x32x16_bf16 v[20:35], v[48:51], v[44:47], v[20:35]
	s_setprio 0
	v_add_f32_e32 v168, v168, v169
	v_add_f32_e32 v191, v168, v191
	s_branch .LBB0_1114
